# single-counter fast path for the two local group seams (no ticket round trip): add + poll same XCC sub-counter against locally known generation
# baseline (speedup 1.0000x reference)
.LBB0_513:
	s_waitcnt lgkmcnt(0)
	v_cmp_eq_u32_e32 vcc, 1, v2
	s_cbranch_vccz .Lseam_slow_1
	v_readlane_b32 s4, v253, 37
	v_readlane_b32 s5, v253, 38
	v_readlane_b32 s11, v250, 21
	v_mov_b32_e32 v4, 1
	s_add_i32 s11, s11, 2
	v_mul_lo_u32 v5, v3, s11
	s_mov_b32 s11, 0
	s_nop 1
	global_atomic_add v27, v4, s[4:5]
.Lseam_poll_1:
	global_load_dword v6, v27, s[4:5] sc1
	s_waitcnt vmcnt(0)
	v_cmp_ge_u32_e32 vcc, v6, v5
	s_cbranch_vccnz .Lseam_rel_1
	s_sleep 1
	s_add_i32 s11, s11, 1
	s_cmp_lt_u32 s11, 0x40000
	s_cbranch_scc1 .Lseam_poll_1
.Lseam_rel_1:
	s_mov_b64 s[20:21], 0
	v_readlane_b32 s4, v252, 31
	v_readlane_b32 s5, v252, 32
	s_andn2_b64 vcc, exec, s[4:5]
	s_cbranch_vccnz .LBB0_536
	v_readlane_b32 s4, v253, 39
	v_readlane_b32 s5, v253, 40
	s_nop 4
	global_atomic_add v27, v4, s[4:5]
	s_branch .LBB0_532

.LBB0_636:
	s_waitcnt lgkmcnt(0)
	v_cmp_eq_u32_e32 vcc, 1, v2
	s_cbranch_vccz .Lseam_slow_2
	v_readlane_b32 s4, v253, 37
	v_readlane_b32 s5, v253, 38
	v_readlane_b32 s11, v250, 21
	v_mov_b32_e32 v4, 1
	s_add_i32 s11, s11, 3
	v_mul_lo_u32 v5, v3, s11
	s_mov_b32 s11, 0
	s_nop 1
	global_atomic_add v27, v4, s[4:5]
